# RG-LRU mixer phases: waves 0-3 run at static s_setprio 1 for the whole phase (asymmetric wave priority), on top of the IN-phase static priority
# speedup vs baseline: 1.0062x; 1.0005x over previous
.LBB0_634:
	s_andn2_b64 vcc, exec, s[2:3]
	s_cbranch_vccnz .LBB0_1177
	v_readlane_b32 s0, v254, 29
	s_cmp_lt_i32 s0, 3
	s_mov_b64 s[2:3], -1
	s_cbranch_scc1 .LBB0_869
	s_cmp_eq_u32 s0, 3
	s_cbranch_scc0 .LBB0_868
	v_readfirstlane_b32 s101, v0
	s_cmp_ge_u32 s101, 0x100
	s_cbranch_scc1 .Lmy_lru_prio
	s_setprio 1
.Lmy_lru_prio:
	v_mov_b32_e32 v204, v0
	v_readlane_b32 s0, v254, 28
	v_readlane_b32 s4, v253, 0
	s_and_b32 s1, s0, 7
	s_cmp_lg_u32 s1, 0
	v_readfirstlane_b32 s59, v204
	s_cbranch_scc1 .LBB0_639
	s_ashr_i32 s1, s4, 31
	s_lshr_b32 s1, s1, 29
	s_add_i32 s1, s4, s1
	s_ashr_i32 s2, s1, 3
	s_and_b32 s1, s1, -8
	s_ashr_i32 s0, s0, 3
	s_sub_i32 s1, s4, s1
	s_mul_i32 s0, s1, s0
	s_add_i32 s4, s0, s2
